# attention MLA loop: packed f32 row-sums, direct QK accumulate without negm copies; ffn_up K-loop skips clamped duplicate loads in last iteration; ffn_up epilogue counted waits
# speedup vs baseline: 1.0083x; 1.0083x over previous
; #define LAS __attribute__((address_space(3)))
; DI unsigned pk2(float a, float b) { f32x2 v = {a, b}; bf16x2_t r = __builtin_convertvector(v, bf16x2_t); return __builtin_bit_cast(unsigned, r); }
; DI f32x16 mfma(bf16x8 a, bf16x8 b, f32x16 c) { return __builtin_amdgcn_mfma_f32_32x32x16_bf16(a, b, c, 0, 0, 0); }
; DI float ex2(float x) { return __builtin_amdgcn_exp2f(x); }
; template <int DQK>
; DI void attn_unit(int tid, char* lds, const u16* Qp, const u16* K1, const u16* V1, int nt1, int kpos0, const u16* K2, const u16* V2, int nt2, int qpos0, bool mask, float m_init, float l_init, u16* Op) {
;     ...
; #pragma unroll
;     for (int r = 0; r < 16; ++r) { c0[r] = ex2(c0[r]); c1[r] = ex2(c1[r]); ls += c0[r] + c1[r]; }
;     lrun += ls;
;     bf16x8 pb[4];
;     { u32x4 w = {pk2(c0[0], c0[1]), pk2(c0[2], c0[3]), pk2(c0[4], c0[5]), pk2(c0[6], c0[7])}; pb[0] = __builtin_bit_cast(bf16x8, w); }
;     { u32x4 w = {pk2(c0[8], c0[9]), pk2(c0[10], c0[11]), pk2(c0[12], c0[13]), pk2(c0[14], c0[15])}; pb[1] = __builtin_bit_cast(bf16x8, w); }
;     { u32x4 w = {pk2(c1[0], c1[1]), pk2(c1[2], c1[3]), pk2(c1[4], c1[5]), pk2(c1[6], c1[7])}; pb[2] = __builtin_bit_cast(bf16x8, w); }
;     { u32x4 w = {pk2(c1[8], c1[9]), pk2(c1[10], c1[11]), pk2(c1[12], c1[13]), pk2(c1[14], c1[15])}; pb[3] = __builtin_bit_cast(bf16x8, w); }
;     LAS char* Vb = (LAS char*)(lds + s_cur * SB + KB + vrb);
; #pragma unroll
;     for (int ks = 0; ks < 4; ++ks) {
;       const s16x4 l0 = __builtin_amdgcn_ds_read_tr16_b64_v4i16((LAS s16x4*)(Vb + ((2 * ks) * 2 + 0) * 512));
;       const s16x4 h0 = __builtin_amdgcn_ds_read_tr16_b64_v4i16((LAS s16x4*)(Vb + ((2 * ks + 1) * 2 + 0) * 512));
;       const s16x4 l1 = __builtin_amdgcn_ds_read_tr16_b64_v4i16((LAS s16x4*)(Vb + ((2 * ks) * 2 + 1) * 512));
;       const s16x4 h1 = __builtin_amdgcn_ds_read_tr16_b64_v4i16((LAS s16x4*)(Vb + ((2 * ks + 1) * 2 + 1) * 512));
;       const bf16x8 va0 = {l0[0], l0[1], l0[2], l0[3], h0[0], h0[1], h0[2], h0[3]};
;       const bf16x8 va1 = {l1[0], l1[1], l1[2], l1[3], h1[0], h1[1], h1[2], h1[3]};
;       o0 = mfma(va0, pb[ks], o0); o1 = mfma(va1, pb[ks], o1);
;     }
;     }
;     if (has_wr) sw(s_wr);
.LBB0_684:
.LBB0_685:
	s_mul_i32 s0, s20, 0x5400
	s_add_i32 s26, s0, 0
	v_add_u32_e32 v0, s26, v241
	v_exp_f32_e32 v130, v50
	v_exp_f32_e32 v146, v66
	v_exp_f32_e32 v131, v51
	v_exp_f32_e32 v147, v67
	v_exp_f32_e32 v132, v52
	v_exp_f32_e32 v148, v68
	v_exp_f32_e32 v133, v53
	v_exp_f32_e32 v149, v69
	v_exp_f32_e32 v134, v54
	v_exp_f32_e32 v150, v70
	v_exp_f32_e32 v135, v55
	v_exp_f32_e32 v151, v71
	v_exp_f32_e32 v136, v56
	v_exp_f32_e32 v152, v72
	v_exp_f32_e32 v137, v57
	v_exp_f32_e32 v153, v73
	ds_read_b64_tr_b16 v[66:67], v0 offset:13568
	ds_read_b64_tr_b16 v[68:69], v0 offset:14592
	ds_read_b64_tr_b16 v[70:71], v0 offset:14080
	ds_read_b64_tr_b16 v[72:73], v0 offset:15104
	v_exp_f32_e32 v142, v62
	v_exp_f32_e32 v143, v63
	v_exp_f32_e32 v144, v64
	v_exp_f32_e32 v145, v65
	v_cvt_pk_bf16_f32 v62, v130, v131
	v_cvt_pk_bf16_f32 v63, v132, v133
	v_cvt_pk_bf16_f32 v64, v134, v135
	v_cvt_pk_bf16_f32 v65, v136, v137
	v_exp_f32_e32 v138, v58
	v_exp_f32_e32 v139, v59
	s_waitcnt lgkmcnt(2)
	v_mfma_f32_32x32x16_bf16 v[18:33], v[66:69], v[62:65], v[18:33]
	v_exp_f32_e32 v140, v60
	v_exp_f32_e32 v141, v61
	v_cvt_pk_bf16_f32 v58, v138, v139
	v_cvt_pk_bf16_f32 v60, v142, v143
	v_cvt_pk_bf16_f32 v61, v144, v145
	v_cvt_pk_bf16_f32 v59, v140, v141
	v_cvt_pk_bf16_f32 v54, v146, v147
	s_waitcnt lgkmcnt(0)
	v_mfma_f32_32x32x16_bf16 v[2:17], v[70:73], v[62:65], v[2:17]
	ds_read_b64_tr_b16 v[62:63], v0 offset:15616
	ds_read_b64_tr_b16 v[64:65], v0 offset:16640
	ds_read_b64_tr_b16 v[66:67], v0 offset:16128
	ds_read_b64_tr_b16 v[68:69], v0 offset:17152
	v_cvt_pk_bf16_f32 v55, v148, v149
	v_cvt_pk_bf16_f32 v56, v150, v151
	v_cvt_pk_bf16_f32 v57, v152, v153
	v_exp_f32_e32 v154, v74
	v_exp_f32_e32 v155, v75
	v_exp_f32_e32 v156, v76
	s_waitcnt lgkmcnt(2)
	v_mfma_f32_32x32x16_bf16 v[18:33], v[62:65], v[58:61], v[18:33]
	v_exp_f32_e32 v157, v77
	v_exp_f32_e32 v158, v78
	v_exp_f32_e32 v159, v79
	v_exp_f32_e32 v160, v80
	v_exp_f32_e32 v161, v81
	v_cvt_pk_bf16_f32 v50, v154, v155
	v_cvt_pk_bf16_f32 v51, v156, v157
	s_waitcnt lgkmcnt(0)
	v_mfma_f32_32x32x16_bf16 v[2:17], v[66:69], v[58:61], v[2:17]
	ds_read_b64_tr_b16 v[58:59], v0 offset:17664
	ds_read_b64_tr_b16 v[60:61], v0 offset:18688
	ds_read_b64_tr_b16 v[62:63], v0 offset:18176
	ds_read_b64_tr_b16 v[64:65], v0 offset:19200
	v_cvt_pk_bf16_f32 v52, v158, v159
	v_cvt_pk_bf16_f32 v53, v160, v161
	s_andn2_b64 vcc, exec, s[16:17]
	s_mul_i32 s27, s23, 0x5400
	s_waitcnt lgkmcnt(2)
	v_mfma_f32_32x32x16_bf16 v[18:33], v[58:61], v[54:57], v[18:33]
	s_waitcnt lgkmcnt(0)
	v_mfma_f32_32x32x16_bf16 v[2:17], v[62:65], v[54:57], v[2:17]
	ds_read_b64_tr_b16 v[54:55], v0 offset:19712
	ds_read_b64_tr_b16 v[56:57], v0 offset:20736
	ds_read_b64_tr_b16 v[58:59], v0 offset:20224
	ds_read_b64_tr_b16 v[60:61], v0 offset:21248
	v_cndmask_b32_e64 v0, 0, 1, s[16:17]
	v_cmp_ne_u32_e64 s[0:1], 1, v0
	s_waitcnt lgkmcnt(2)
	v_mfma_f32_32x32x16_bf16 v[18:33], v[54:57], v[50:53], v[18:33]
	s_waitcnt lgkmcnt(0)
	v_mfma_f32_32x32x16_bf16 v[2:17], v[58:61], v[50:53], v[2:17]
	s_cbranch_vccnz .LBB0_689
	s_add_i32 s28, s27, 0
	v_add_u32_e32 v0, s28, v246
	s_waitcnt vmcnt(2)
	ds_write_b128 v0, v[186:189] offset:256
	s_and_saveexec_b64 s[16:17], s[8:9]
	s_cbranch_execz .LBB0_688
	v_add_u32_e32 v0, s28, v245
	s_waitcnt vmcnt(1)
	ds_write_b128 v0, v[190:193] offset:256

; DI f32x16 mfma(bf16x8 a, bf16x8 b, f32x16 c) { return __builtin_amdgcn_mfma_f32_32x32x16_bf16(a, b, c, 0, 0, 0); }
; template <int DQK>
; DI void attn_unit(int tid, char* lds, const u16* Qp, const u16* K1, const u16* V1, int nt1, int kpos0, const u16* K2, const u16* V2, int nt2, int qpos0, bool mask, float m_init, float l_init, u16* Op) {
;     ...
;   auto qk = [&](int st, f32x16& p0, f32x16& p1) {
;     const char* Kb = lds + st * SB + kro;
; #pragma unroll
;     for (int d0 = 0; d0 < ND; ++d0) {
;       const bf16x8 a0 = *(const bf16x8*)(Kb + d0 * 32);
;       const bf16x8 a1 = *(const bf16x8*)(Kb + 32 * KP + d0 * 32);
;       if (d0 == 0) { p0 = mfma(a0, qr[0], negm); p1 = mfma(a1, qr[0], negm); } else { p0 = mfma(a0, qr[d0], p0); p1 = mfma(a1, qr[d0], p1); }
;     }
;   };
.LBB0_691:
	s_and_b64 vcc, exec, s[0:1]
	s_cbranch_vccnz .LBB0_693
	v_add_u32_e32 v0, s27, v247
	ds_read_b128 v[114:117], v0 offset:256
	ds_read_b128 v[118:121], v0 offset:6912
	ds_read_b128 v[122:125], v0 offset:288
	s_waitcnt lgkmcnt(2)
	v_mfma_f32_32x32x16_bf16 v[50:65], v[114:117], v[162:165], v[34:49]
	ds_read_b128 v[114:117], v0 offset:6944
	s_waitcnt lgkmcnt(2)
	v_mfma_f32_32x32x16_bf16 v[66:81], v[118:121], v[162:165], v[34:49]
	ds_read_b128 v[118:121], v0 offset:320
	s_waitcnt lgkmcnt(2)
	v_mfma_f32_32x32x16_bf16 v[50:65], v[122:125], v[166:169], v[50:65]
	ds_read_b128 v[122:125], v0 offset:6976
	s_waitcnt lgkmcnt(2)
	v_mfma_f32_32x32x16_bf16 v[66:81], v[114:117], v[166:169], v[66:81]
	ds_read_b128 v[114:117], v0 offset:352
	s_waitcnt lgkmcnt(2)
	v_mfma_f32_32x32x16_bf16 v[50:65], v[118:121], v[170:173], v[50:65]
	ds_read_b128 v[118:121], v0 offset:7008
	s_waitcnt lgkmcnt(2)
	v_mfma_f32_32x32x16_bf16 v[66:81], v[122:125], v[170:173], v[66:81]
	ds_read_b128 v[122:125], v0 offset:384
	s_waitcnt lgkmcnt(2)
	v_mfma_f32_32x32x16_bf16 v[50:65], v[114:117], v[174:177], v[50:65]
	ds_read_b128 v[114:117], v0 offset:7040
	s_waitcnt lgkmcnt(2)
	v_mfma_f32_32x32x16_bf16 v[66:81], v[118:121], v[174:177], v[66:81]
	ds_read_b128 v[118:121], v0 offset:416
	s_waitcnt lgkmcnt(2)
	v_mfma_f32_32x32x16_bf16 v[50:65], v[122:125], v[178:181], v[50:65]
	ds_read_b128 v[122:125], v0 offset:7072
	s_waitcnt lgkmcnt(2)
	v_mfma_f32_32x32x16_bf16 v[66:81], v[114:117], v[178:181], v[66:81]
	s_waitcnt lgkmcnt(1)
	v_mfma_f32_32x32x16_bf16 v[50:65], v[118:121], v[182:185], v[50:65]
	s_waitcnt lgkmcnt(0)
	v_mfma_f32_32x32x16_bf16 v[66:81], v[122:125], v[182:185], v[66:81]
	s_branch .LBB0_694

; DI float ex2(float x) { return __builtin_amdgcn_exp2f(x); }
; DI float xmax32(float v) { auto rr = __builtin_amdgcn_permlane32_swap(__float_as_uint(v), __float_as_uint(v), false, false); return fmaxf(__uint_as_float(rr[0]), __uint_as_float(rr[1])); }
; template <int DQK>
; DI void attn_unit(int tid, char* lds, const u16* Qp, const u16* K1, const u16* V1, int nt1, int kpos0, const u16* K2, const u16* V2, int nt2, int qpos0, bool mask, float m_init, float l_init, u16* Op) {
;     ...
;     float mt = c0[0];
; #pragma unroll
;     for (int r = 1; r < 16; ++r) mt = fmaxf(mt, c0[r]);
; #pragma unroll
;     for (int r = 0; r < 16; ++r) mt = fmaxf(mt, c1[r]);
;     mt = xmax32(mt);
;     if (__any(mt > THR)) {
;       const float delta = fmaxf(mt, 0.f), alpha = ex2(-delta);
;       mrun += delta; lrun *= alpha;
; #pragma unroll
;       for (int r = 0; r < 16; ++r) { o0[r] *= alpha; o1[r] *= alpha; c0[r] -= delta; c1[r] -= delta; n0[r] -= delta; n1[r] -= delta; negm[r] = -mrun; }
;     }
;     float ls = 0.f;
; #pragma unroll
;     for (int r = 0; r < 16; ++r) { c0[r] = ex2(c0[r]); c1[r] = ex2(c1[r]); ls += c0[r] + c1[r]; }
;     lrun += ls;
.LBB0_694:
	v_pk_add_f32 v[126:127], v[130:131], v[132:133]
	v_pk_add_f32 v[128:129], v[134:135], v[136:137]
	v_pk_add_f32 v[126:127], v[126:127], v[138:139]
	v_pk_add_f32 v[128:129], v[128:129], v[140:141]
	v_pk_add_f32 v[126:127], v[126:127], v[142:143]
	v_pk_add_f32 v[128:129], v[128:129], v[144:145]
	v_pk_add_f32 v[126:127], v[126:127], v[146:147]
	v_pk_add_f32 v[128:129], v[128:129], v[148:149]
	v_pk_add_f32 v[126:127], v[126:127], v[150:151]
	v_pk_add_f32 v[128:129], v[128:129], v[152:153]
	v_pk_add_f32 v[126:127], v[126:127], v[154:155]
	v_pk_add_f32 v[128:129], v[128:129], v[156:157]
	v_pk_add_f32 v[126:127], v[126:127], v[158:159]
	v_pk_add_f32 v[128:129], v[128:129], v[160:161]
	v_pk_add_f32 v[126:127], v[126:127], v[128:129]
	v_add_f32_e32 v0, v126, v127
	v_max_f32_e32 v114, v83, v83
	v_max_f32_e32 v115, v82, v82
	v_max_f32_e32 v114, v115, v114
	v_max3_f32 v114, v114, v84, v85
	v_max3_f32 v114, v114, v86, v87
	v_max3_f32 v114, v114, v88, v89
	v_max3_f32 v114, v114, v90, v91
	v_max3_f32 v114, v114, v92, v93
	v_max3_f32 v114, v114, v94, v95
	v_max3_f32 v114, v114, v96, v97
	v_max3_f32 v114, v114, v98, v99
	v_max3_f32 v114, v114, v100, v101
	v_max3_f32 v114, v114, v102, v103
	v_max3_f32 v114, v114, v104, v105
	v_max3_f32 v114, v114, v106, v107
	v_max3_f32 v114, v114, v108, v109
	v_max3_f32 v114, v114, v110, v111
	v_max3_f32 v114, v114, v112, v113
	v_mov_b32_e32 v115, v114
	s_nop 1
	v_permlane32_swap_b32_e32 v114, v115
	v_max_f32_e32 v115, v115, v115
	v_max_f32_e32 v114, v114, v114
	v_max_f32_e32 v114, v114, v115
	v_add_f32_e32 v0, v215, v0
	v_cmp_lt_f32_e32 vcc, s2, v114
	s_cbranch_vccz .LBB0_696
	v_max_f32_e32 v34, v114, v114
	v_max_f32_e32 v36, 0, v34
	v_exp_f32_e64 v38, -v36
	v_add_f32_e32 v216, v216, v36
	v_xor_b32_e32 v34, 0x80000000, v216
	v_pk_add_f32 v[82:83], v[82:83], v[36:37] op_sel_hi:[1,0] neg_lo:[0,1] neg_hi:[0,1]
	v_mul_f32_e32 v0, v0, v38
	v_pk_add_f32 v[98:99], v[98:99], v[36:37] op_sel_hi:[1,0] neg_lo:[0,1] neg_hi:[0,1]
	v_pk_add_f32 v[84:85], v[84:85], v[36:37] op_sel_hi:[1,0] neg_lo:[0,1] neg_hi:[0,1]
	v_pk_add_f32 v[100:101], v[100:101], v[36:37] op_sel_hi:[1,0] neg_lo:[0,1] neg_hi:[0,1]
	v_pk_add_f32 v[86:87], v[86:87], v[36:37] op_sel_hi:[1,0] neg_lo:[0,1] neg_hi:[0,1]
	v_pk_add_f32 v[102:103], v[102:103], v[36:37] op_sel_hi:[1,0] neg_lo:[0,1] neg_hi:[0,1]
	v_pk_add_f32 v[88:89], v[88:89], v[36:37] op_sel_hi:[1,0] neg_lo:[0,1] neg_hi:[0,1]
	v_pk_add_f32 v[104:105], v[104:105], v[36:37] op_sel_hi:[1,0] neg_lo:[0,1] neg_hi:[0,1]
	v_pk_add_f32 v[90:91], v[90:91], v[36:37] op_sel_hi:[1,0] neg_lo:[0,1] neg_hi:[0,1]
	v_pk_add_f32 v[106:107], v[106:107], v[36:37] op_sel_hi:[1,0] neg_lo:[0,1] neg_hi:[0,1]
	v_pk_add_f32 v[92:93], v[92:93], v[36:37] op_sel_hi:[1,0] neg_lo:[0,1] neg_hi:[0,1]
	v_pk_add_f32 v[108:109], v[108:109], v[36:37] op_sel_hi:[1,0] neg_lo:[0,1] neg_hi:[0,1]
	v_pk_add_f32 v[94:95], v[94:95], v[36:37] op_sel_hi:[1,0] neg_lo:[0,1] neg_hi:[0,1]
	v_pk_add_f32 v[110:111], v[110:111], v[36:37] op_sel_hi:[1,0] neg_lo:[0,1] neg_hi:[0,1]
	v_pk_mul_f32 v[32:33], v[32:33], v[38:39] op_sel_hi:[1,0]
	v_pk_mul_f32 v[30:31], v[30:31], v[38:39] op_sel_hi:[1,0]
	v_pk_mul_f32 v[28:29], v[28:29], v[38:39] op_sel_hi:[1,0]
	v_pk_mul_f32 v[26:27], v[26:27], v[38:39] op_sel_hi:[1,0]
	v_pk_mul_f32 v[24:25], v[24:25], v[38:39] op_sel_hi:[1,0]
	v_pk_mul_f32 v[22:23], v[22:23], v[38:39] op_sel_hi:[1,0]
	v_pk_mul_f32 v[20:21], v[20:21], v[38:39] op_sel_hi:[1,0]
	v_pk_mul_f32 v[18:19], v[18:19], v[38:39] op_sel_hi:[1,0]
	v_pk_mul_f32 v[16:17], v[16:17], v[38:39] op_sel_hi:[1,0]
	v_pk_mul_f32 v[14:15], v[14:15], v[38:39] op_sel_hi:[1,0]
	v_pk_mul_f32 v[12:13], v[12:13], v[38:39] op_sel_hi:[1,0]
	v_pk_mul_f32 v[10:11], v[10:11], v[38:39] op_sel_hi:[1,0]
	v_pk_mul_f32 v[8:9], v[8:9], v[38:39] op_sel_hi:[1,0]
	v_pk_mul_f32 v[6:7], v[6:7], v[38:39] op_sel_hi:[1,0]
	v_pk_mul_f32 v[4:5], v[4:5], v[38:39] op_sel_hi:[1,0]
	v_pk_mul_f32 v[2:3], v[2:3], v[38:39] op_sel_hi:[1,0]
	v_pk_add_f32 v[96:97], v[96:97], v[36:37] op_sel_hi:[1,0] neg_lo:[0,1] neg_hi:[0,1]
	v_pk_add_f32 v[112:113], v[112:113], v[36:37] op_sel_hi:[1,0] neg_lo:[0,1] neg_hi:[0,1]
	v_sub_f32_e32 v65, v65, v36
	v_sub_f32_e32 v64, v64, v36
	v_sub_f32_e32 v63, v63, v36
	v_sub_f32_e32 v62, v62, v36
	v_sub_f32_e32 v61, v61, v36
	v_sub_f32_e32 v60, v60, v36
	v_sub_f32_e32 v59, v59, v36
	v_sub_f32_e32 v58, v58, v36
	v_sub_f32_e32 v57, v57, v36
	v_sub_f32_e32 v56, v56, v36
	v_sub_f32_e32 v55, v55, v36
	v_sub_f32_e32 v54, v54, v36
	v_sub_f32_e32 v53, v53, v36
	v_sub_f32_e32 v52, v52, v36
	v_sub_f32_e32 v51, v51, v36
	v_sub_f32_e32 v50, v50, v36
	v_sub_f32_e32 v81, v81, v36
	v_sub_f32_e32 v80, v80, v36
	v_sub_f32_e32 v79, v79, v36
	v_sub_f32_e32 v78, v78, v36
	v_sub_f32_e32 v77, v77, v36
	v_sub_f32_e32 v76, v76, v36
	v_sub_f32_e32 v75, v75, v36
	v_sub_f32_e32 v74, v74, v36
	v_sub_f32_e32 v73, v73, v36
	v_sub_f32_e32 v72, v72, v36
	v_sub_f32_e32 v71, v71, v36
	v_sub_f32_e32 v70, v70, v36
	v_sub_f32_e32 v69, v69, v36
	v_sub_f32_e32 v68, v68, v36
	v_sub_f32_e32 v67, v67, v36
	v_sub_f32_e32 v66, v66, v36
	v_mov_b32_e32 v35, v34
	v_mov_b32_e32 v36, v34
	v_mov_b32_e32 v37, v34
	v_mov_b32_e32 v38, v34
	v_mov_b32_e32 v39, v34
	v_mov_b32_e32 v40, v34
	v_mov_b32_e32 v41, v34
	v_mov_b32_e32 v42, v34
	v_mov_b32_e32 v43, v34
	v_mov_b32_e32 v44, v34
	v_mov_b32_e32 v45, v34
	v_mov_b32_e32 v46, v34
	v_mov_b32_e32 v47, v34
	v_mov_b32_e32 v48, v34
	v_mov_b32_e32 v49, v34

; DI float ex2(float x) { return __builtin_amdgcn_exp2f(x); }
; template <int DQK>
; DI void attn_unit(int tid, char* lds, const u16* Qp, const u16* K1, const u16* V1, int nt1, int kpos0, const u16* K2, const u16* V2, int nt2, int qpos0, bool mask, float m_init, float l_init, u16* Op) {
;     ...
;     float ls = 0.f;
; #pragma unroll
;     for (int r = 0; r < 16; ++r) { c0[r] = ex2(c0[r]); c1[r] = ex2(c1[r]); ls += c0[r] + c1[r]; }
;     lrun += ls;
;     ...
;   for (int i = 0; i < NT; i += 2) {
;     step(pA0, pA1, pB0, pB1, i, s_cur, s_nxt, s_wr);
;     if (i + 1 >= NT) break;
;     step(pB0, pB1, pA0, pA1, i + 1, s_nxt, s_wr, s_cur);
;     const int t_ = s_cur; s_cur = s_wr; s_wr = s_nxt; s_nxt = t_;
;   }
.LBB0_700:
	v_pk_add_f32 v[130:131], v[94:95], v[96:97]
	v_pk_add_f32 v[132:133], v[98:99], v[100:101]
	v_pk_add_f32 v[130:131], v[130:131], v[102:103]
	v_pk_add_f32 v[132:133], v[132:133], v[104:105]
	v_pk_add_f32 v[130:131], v[130:131], v[106:107]
	v_pk_add_f32 v[132:133], v[132:133], v[108:109]
	v_pk_add_f32 v[130:131], v[130:131], v[110:111]
	v_pk_add_f32 v[132:133], v[132:133], v[112:113]
	v_pk_add_f32 v[130:131], v[130:131], v[114:115]
	v_pk_add_f32 v[132:133], v[132:133], v[116:117]
	v_pk_add_f32 v[130:131], v[130:131], v[118:119]
	v_pk_add_f32 v[132:133], v[132:133], v[120:121]
	v_pk_add_f32 v[130:131], v[130:131], v[122:123]
	v_pk_add_f32 v[132:133], v[132:133], v[124:125]
	v_pk_add_f32 v[130:131], v[130:131], v[132:133]
	v_add_f32_e32 v82, v130, v131
	s_add_i32 s22, s22, 2
	v_add_f32_e32 v215, v0, v82
	s_cmpk_lt_u32 s24, 0x82
	s_waitcnt lgkmcnt(0)
	s_barrier
	s_cbranch_scc0 .LBB0_550
	s_mov_b32 s0, s21
	s_mov_b32 s21, s20
	s_mov_b32 s20, s23
	s_branch .LBB0_680

; #define GLOAD(RA, RB, KT) do { const int kc_ = (KT) * 8 + lc; _Pragma("unroll") for (int j = 0; j < NA; ++j) RA[j] = al.load(j, kc_); _Pragma("unroll") for (int j = 0; j < NB; ++j) RB[j] = bl.load(j, kc_); } while (0)
; #define LWRITE(RA, RB, BUF) do { char* w_ = wa + (BUF) * STAGE; _Pragma("unroll") for (int j = 0; j < NA; ++j) *(u32x4*)(w_ + j * 64 * PITCH) = RA[j]; _Pragma("unroll") for (int j = 0; j < NB; ++j) *(u32x4*)(w_ + AB + j * 64 * PITCH) = RB[j]; } while (0)
; #define GLOAD(RA, RB, KT) do { const int kc_ = (KT) * 8 + lc; _Pragma("unroll") for (int j = 0; j < NA; ++j) RA[j] = al.load(j, kc_); _Pragma("unroll") for (int j = 0; j < NB; ++j) RB[j] = bl.load(j, kc_); } while (0)
; #define LWRITE(RA, RB, BUF) do { char* w_ = wa + (BUF) * STAGE; _Pragma("unroll") for (int j = 0; j < NA; ++j) *(u32x4*)(w_ + j * 64 * RB_) = RA[j]; _Pragma("unroll") for (int j = 0; j < NB; ++j) *(u32x4*)(w_ + AB + j * 64 * RB_) = RB[j]; } while (0)
; #define COMPUTE(BUF, RA, RB, WBUF) do { const char* sb = lds + (BUF) * STAGE; char* w_ = wa + (WBUF) * STAGE; \
;     KSTEP(o0); *(u32x4*)(w_) = RA[0]; *(u32x4*)(w_ + 64 * RB_) = RA[1]; *(u32x4*)(w_ + 128 * RB_) = RA[2]; \
;     KSTEP(o1); *(u32x4*)(w_ + 192 * RB_) = RA[3]; *(u32x4*)(w_ + AB) = RB[0]; *(u32x4*)(w_ + AB + 64 * RB_) = RB[1]; } while (0)
; template <bool SW, class AL, class BL>
; DI void gemm_run16(int tid, char* lds, const AL& al, const BL& bl, int nk, f32x4 (&acc)[4][4], u32x4 (&ra0)[4], u32x4 (&rb0)[2], u32x4 (&ra1)[4], u32x4 (&rb1)[2]) {
;     ...
;   const int kl = nk - 1;
;   LWRITE(ra0, rb0, 0);
;   __syncthreads();
; #pragma unroll 1
;   for (int kt = 0; kt < nk; kt += 2) {
;     GLOAD(ra0, rb0, (kt + 2 < kl ? kt + 2 : kl));
;     COMPUTE(0, ra1, rb1, 1);
;     __syncthreads();
;     if (kt + 1 >= nk) break;
;     GLOAD(ra1, rb1, (kt + 3 < kl ? kt + 3 : kl));
;     COMPUTE(1, ra0, rb0, 0);
;     __syncthreads();
.LBB0_1060:
	v_add_u32_e32 v0, v144, v142
	v_add_u32_e32 v132, v145, v142
	ds_read_b128 v[26:29], v0 offset:35072
	ds_read_b128 v[30:33], v0 offset:37120
	ds_read_b128 v[34:37], v132 offset:2304
	ds_read_b128 v[38:41], v132 offset:4352
	ds_read_b128 v[46:49], v0 offset:39168
	v_add_u32_e32 v133, v145, v143
	s_waitcnt lgkmcnt(2)
	v_mfma_f32_16x16x32_bf16 v[42:45], v[26:29], v[34:37], v[50:53]
	s_add_i32 s19, s18, 4
	s_min_u32 s19, s19, 15
	v_mfma_f32_16x16x32_bf16 v[50:53], v[30:33], v[34:37], v[54:57]
	s_nop 2
	ds_read_b128 v[54:57], v0 offset:41216
	s_waitcnt lgkmcnt(1)
	v_mfma_f32_16x16x32_bf16 v[58:61], v[46:49], v[34:37], v[58:61]
	v_add_u32_e32 v0, v144, v143
	s_waitcnt lgkmcnt(0)
	v_mfma_f32_16x16x32_bf16 v[34:37], v[54:57], v[34:37], v[62:65]
	v_mfma_f32_16x16x32_bf16 v[62:65], v[26:29], v[38:41], v[66:69]
	v_mfma_f32_16x16x32_bf16 v[66:69], v[30:33], v[38:41], v[70:73]
	v_mfma_f32_16x16x32_bf16 v[70:73], v[46:49], v[38:41], v[74:77]
	v_mfma_f32_16x16x32_bf16 v[38:41], v[54:57], v[38:41], v[78:81]
	s_nop 1
	ds_read_b128 v[74:77], v132 offset:6400
	ds_read_b128 v[78:81], v132 offset:8448
	s_waitcnt vmcnt(5)
	ds_write_b128 v141, v[14:17] offset:51456
	s_waitcnt vmcnt(4)
	ds_write_b128 v141, v[18:21] offset:59648
	s_waitcnt vmcnt(3)
	ds_write_b128 v146, v[22:25]
	ds_read_b128 v[18:21], v0 offset:35072
	ds_read_b128 v[22:25], v0 offset:37120
	s_waitcnt lgkmcnt(6)
	v_mfma_f32_16x16x32_bf16 v[82:85], v[26:29], v[74:77], v[82:85]
	v_mfma_f32_16x16x32_bf16 v[86:89], v[30:33], v[74:77], v[86:89]
	v_mfma_f32_16x16x32_bf16 v[90:93], v[46:49], v[74:77], v[90:93]
	v_mfma_f32_16x16x32_bf16 v[74:77], v[54:57], v[74:77], v[94:97]
	s_waitcnt lgkmcnt(5)
	v_mfma_f32_16x16x32_bf16 v[94:97], v[26:29], v[78:81], v[102:105]
	v_mfma_f32_16x16x32_bf16 v[98:101], v[30:33], v[78:81], v[98:101]
	ds_read_b128 v[26:29], v133 offset:2304
	ds_read_b128 v[30:33], v133 offset:4352
	ds_read_b128 v[102:105], v0 offset:39168
	ds_read_b128 v[136:139], v133 offset:8448
	v_mfma_f32_16x16x32_bf16 v[14:17], v[46:49], v[78:81], v[106:109]
	s_nop 2
	ds_read_b128 v[106:109], v0 offset:41216
	v_mfma_f32_16x16x32_bf16 v[54:57], v[54:57], v[78:81], v[110:113]
	v_lshl_or_b32 v0, s19, 7, v122
	v_lshl_add_u64 v[46:47], v[130:131], 0, v[0:1]
	s_add_i32 s19, s18, 2
	s_waitcnt lgkmcnt(4)
	v_mfma_f32_16x16x32_bf16 v[78:81], v[18:21], v[26:29], v[42:45]
	s_min_u32 s18, s19, 12
	s_cmp_lt_u32 s19, 14
	v_mfma_f32_16x16x32_bf16 v[50:53], v[22:25], v[26:29], v[50:53]
	v_lshl_add_u64 v[42:43], v[128:129], 0, v[0:1]
	s_waitcnt lgkmcnt(2)
	v_mfma_f32_16x16x32_bf16 v[58:61], v[102:105], v[26:29], v[58:61]
	s_waitcnt lgkmcnt(0)
	v_mfma_f32_16x16x32_bf16 v[110:113], v[106:109], v[26:29], v[34:37]
	ds_read_b128 v[26:29], v133 offset:6400
	s_waitcnt vmcnt(2)
	ds_write_b128 v147, v[2:5]
	s_waitcnt vmcnt(1)
	ds_write_b128 v148, v[6:9]
	s_waitcnt vmcnt(0)
	ds_write_b128 v149, v[10:13]
	v_lshl_add_u64 v[34:35], v[124:125], 0, v[0:1]
	v_mfma_f32_16x16x32_bf16 v[62:65], v[18:21], v[30:33], v[62:65]
	v_mfma_f32_16x16x32_bf16 v[66:69], v[22:25], v[30:33], v[66:69]
	v_mfma_f32_16x16x32_bf16 v[70:73], v[102:105], v[30:33], v[70:73]
	v_mfma_f32_16x16x32_bf16 v[114:117], v[106:109], v[30:33], v[38:41]
	v_lshl_add_u64 v[30:31], v[118:119], 0, v[0:1]
	v_lshl_add_u64 v[32:33], v[120:121], 0, v[0:1]
	s_waitcnt lgkmcnt(3)
	v_mfma_f32_16x16x32_bf16 v[82:85], v[18:21], v[26:29], v[82:85]
	v_lshl_add_u64 v[38:39], v[126:127], 0, v[0:1]
	v_lshl_or_b32 v0, s18, 7, v122
	s_mov_b32 s18, s19
	v_mfma_f32_16x16x32_bf16 v[2:5], v[22:25], v[26:29], v[86:89]
	v_mfma_f32_16x16x32_bf16 v[6:9], v[102:105], v[26:29], v[90:93]
	v_mfma_f32_16x16x32_bf16 v[10:13], v[106:109], v[26:29], v[74:77]
	s_cbranch_scc0 .Lffn_skip1
	global_load_dwordx4 v[26:29], v[30:31], off
	s_nop 0
	global_load_dwordx4 v[30:33], v[32:33], off
	s_nop 0
	global_load_dwordx4 v[34:37], v[34:35], off
	s_nop 0
	global_load_dwordx4 v[38:41], v[38:39], off
	s_nop 0
	global_load_dwordx4 v[42:45], v[42:43], off
	s_nop 0
	global_load_dwordx4 v[46:49], v[46:47], off
; #define GLOAD(RA, RB, KT) do { const int kc_ = (KT) * 8 + lc; _Pragma("unroll") for (int j = 0; j < NA; ++j) RA[j] = al.load(j, kc_); _Pragma("unroll") for (int j = 0; j < NB; ++j) RB[j] = bl.load(j, kc_); } while (0)
; #define LWRITE(RA, RB, BUF) do { char* w_ = wa + (BUF) * STAGE; _Pragma("unroll") for (int j = 0; j < NA; ++j) *(u32x4*)(w_ + j * 64 * PITCH) = RA[j]; _Pragma("unroll") for (int j = 0; j < NB; ++j) *(u32x4*)(w_ + AB + j * 64 * PITCH) = RB[j]; } while (0)
; #define GLOAD(RA, RB, KT) do { const int kc_ = (KT) * 8 + lc; _Pragma("unroll") for (int j = 0; j < NA; ++j) RA[j] = al.load(j, kc_); _Pragma("unroll") for (int j = 0; j < NB; ++j) RB[j] = bl.load(j, kc_); } while (0)
; #define LWRITE(RA, RB, BUF) do { char* w_ = wa + (BUF) * STAGE; _Pragma("unroll") for (int j = 0; j < NA; ++j) *(u32x4*)(w_ + j * 64 * RB_) = RA[j]; _Pragma("unroll") for (int j = 0; j < NB; ++j) *(u32x4*)(w_ + AB + j * 64 * RB_) = RB[j]; } while (0)
; #define COMPUTE(BUF, RA, RB, WBUF) do { const char* sb = lds + (BUF) * STAGE; char* w_ = wa + (WBUF) * STAGE; \
;     KSTEP(o0); *(u32x4*)(w_) = RA[0]; *(u32x4*)(w_ + 64 * RB_) = RA[1]; *(u32x4*)(w_ + 128 * RB_) = RA[2]; \
;     KSTEP(o1); *(u32x4*)(w_ + 192 * RB_) = RA[3]; *(u32x4*)(w_ + AB) = RB[0]; *(u32x4*)(w_ + AB + 64 * RB_) = RB[1]; } while (0)
; template <bool SW, class AL, class BL>
; DI void gemm_run16(int tid, char* lds, const AL& al, const BL& bl, int nk, f32x4 (&acc)[4][4], u32x4 (&ra0)[4], u32x4 (&rb0)[2], u32x4 (&ra1)[4], u32x4 (&rb1)[2]) {
;     ...
;   const int kl = nk - 1;
;   LWRITE(ra0, rb0, 0);
;   __syncthreads();
; #pragma unroll 1
;   for (int kt = 0; kt < nk; kt += 2) {
;     GLOAD(ra0, rb0, (kt + 2 < kl ? kt + 2 : kl));
;     COMPUTE(0, ra1, rb1, 1);
;     __syncthreads();
;     if (kt + 1 >= nk) break;
;     GLOAD(ra1, rb1, (kt + 3 < kl ? kt + 3 : kl));
;     COMPUTE(1, ra0, rb0, 0);
;     __syncthreads();
.Lffn_skip1:
	s_waitcnt lgkmcnt(0)
	s_barrier
	ds_read_b128 v[74:77], v153
	ds_read_b128 v[86:89], v153 offset:2048
	v_mfma_f32_16x16x32_bf16 v[18:21], v[18:21], v[136:139], v[94:97]
	ds_read_b128 v[90:93], v132 offset:51456
	s_nop 1
	ds_read_b128 v[94:97], v132 offset:53504
	v_mfma_f32_16x16x32_bf16 v[22:25], v[22:25], v[136:139], v[98:101]
	v_mfma_f32_16x16x32_bf16 v[14:17], v[102:105], v[136:139], v[14:17]
	s_nop 1
	ds_read_b128 v[98:101], v153 offset:4096
	s_waitcnt lgkmcnt(2)
	v_mfma_f32_16x16x32_bf16 v[102:105], v[86:89], v[90:93], v[50:53]
	s_nop 2
	ds_read_b128 v[50:53], v153 offset:6144
	v_mfma_f32_16x16x32_bf16 v[54:57], v[106:109], v[136:139], v[54:57]
	v_mfma_f32_16x16x32_bf16 v[78:81], v[74:77], v[90:93], v[78:81]
	s_waitcnt lgkmcnt(1)
	v_mfma_f32_16x16x32_bf16 v[58:61], v[98:101], v[90:93], v[58:61]
	s_waitcnt lgkmcnt(0)
	v_mfma_f32_16x16x32_bf16 v[90:93], v[50:53], v[90:93], v[110:113]
	v_mfma_f32_16x16x32_bf16 v[106:109], v[74:77], v[94:97], v[62:65]
	v_mfma_f32_16x16x32_bf16 v[110:113], v[86:89], v[94:97], v[66:69]
	s_nop 1
	ds_read_b128 v[62:65], v132 offset:55552
	ds_read_b128 v[66:69], v132 offset:57600
	s_cbranch_scc0 .Lffn_skipw1
	s_waitcnt vmcnt(5)
	ds_write_b128 v141, v[26:29] offset:2304
	s_waitcnt vmcnt(4)
	ds_write_b128 v141, v[30:33] offset:10496
	s_waitcnt vmcnt(3)
	ds_write_b128 v141, v[34:37] offset:18688
	s_branch .Lffn_w1done
.Lffn_skipw1:
	s_waitcnt lgkmcnt(0)
.Lffn_w1done:
	v_mfma_f32_16x16x32_bf16 v[136:139], v[98:101], v[94:97], v[70:73]
	v_mfma_f32_16x16x32_bf16 v[94:97], v[50:53], v[94:97], v[114:117]
	s_waitcnt lgkmcnt(4)
	v_mfma_f32_16x16x32_bf16 v[6:9], v[98:101], v[62:65], v[6:9]
	s_waitcnt lgkmcnt(3)
	v_mfma_f32_16x16x32_bf16 v[114:117], v[74:77], v[66:69], v[18:21]
	v_mfma_f32_16x16x32_bf16 v[158:161], v[86:89], v[66:69], v[22:25]
	v_mfma_f32_16x16x32_bf16 v[162:165], v[98:101], v[66:69], v[14:17]
	s_nop 1
	ds_read_b128 v[22:25], v154
	ds_read_b128 v[98:101], v154 offset:2048
	ds_read_b128 v[14:17], v133 offset:51456
	ds_read_b128 v[18:21], v133 offset:53504
	ds_read_b128 v[170:173], v154 offset:4096
	ds_read_b128 v[174:177], v154 offset:6144
	v_mfma_f32_16x16x32_bf16 v[82:85], v[74:77], v[62:65], v[82:85]
	v_mfma_f32_16x16x32_bf16 v[2:5], v[86:89], v[62:65], v[2:5]
	v_mfma_f32_16x16x32_bf16 v[10:13], v[50:53], v[62:65], v[10:13]
	v_mfma_f32_16x16x32_bf16 v[166:169], v[50:53], v[66:69], v[54:57]
	s_waitcnt lgkmcnt(3)
	v_mfma_f32_16x16x32_bf16 v[50:53], v[22:25], v[14:17], v[78:81]
	v_mfma_f32_16x16x32_bf16 v[54:57], v[98:101], v[14:17], v[102:105]
	s_waitcnt lgkmcnt(1)
	v_mfma_f32_16x16x32_bf16 v[58:61], v[170:173], v[14:17], v[58:61]
	s_waitcnt lgkmcnt(0)
	v_mfma_f32_16x16x32_bf16 v[62:65], v[174:177], v[14:17], v[90:93]
	v_mfma_f32_16x16x32_bf16 v[70:73], v[98:101], v[18:21], v[110:113]
	ds_read_b128 v[14:17], v133 offset:55552
	s_nop 1
	ds_read_b128 v[110:113], v133 offset:57600
	s_waitcnt lgkmcnt(1)
	v_mfma_f32_16x16x32_bf16 v[86:89], v[98:101], v[14:17], v[2:5]
	s_nop 2
	v_lshl_add_u64 v[2:3], v[118:119], 0, v[0:1]
	v_lshl_add_u64 v[4:5], v[120:121], 0, v[0:1]
	v_mfma_f32_16x16x32_bf16 v[90:93], v[170:173], v[14:17], v[6:9]
	s_nop 2
	v_lshl_add_u64 v[6:7], v[124:125], 0, v[0:1]
	v_lshl_add_u64 v[8:9], v[126:127], 0, v[0:1]
	v_mfma_f32_16x16x32_bf16 v[66:69], v[22:25], v[18:21], v[106:109]
	v_mfma_f32_16x16x32_bf16 v[74:77], v[170:173], v[18:21], v[136:139]
	s_nop 1
	v_lshl_add_u64 v[106:107], v[128:129], 0, v[0:1]
	v_mfma_f32_16x16x32_bf16 v[78:81], v[174:177], v[18:21], v[94:97]
	v_mfma_f32_16x16x32_bf16 v[82:85], v[22:25], v[14:17], v[82:85]
	v_mfma_f32_16x16x32_bf16 v[94:97], v[174:177], v[14:17], v[10:13]
	s_waitcnt lgkmcnt(0)
	v_mfma_f32_16x16x32_bf16 v[102:105], v[22:25], v[110:113], v[114:117]
	v_mfma_f32_16x16x32_bf16 v[98:101], v[98:101], v[110:113], v[158:161]
	s_cbranch_scc0 .Lffn_skip2
	v_lshl_add_u64 v[10:11], v[130:131], 0, v[0:1]
	global_load_dwordx4 v[14:17], v[2:3], off offset:384
	global_load_dwordx4 v[18:21], v[4:5], off offset:384
	s_nop 0
	global_load_dwordx4 v[22:25], v[6:7], off offset:384
	global_load_dwordx4 v[2:5], v[8:9], off offset:384
	s_nop 0
	global_load_dwordx4 v[6:9], v[106:107], off offset:384
	s_nop 0
	global_load_dwordx4 v[10:13], v[10:11], off offset:384
	s_waitcnt vmcnt(8)
	ds_write_b128 v141, v[38:41] offset:26880
	s_waitcnt vmcnt(7)
	ds_write_b128 v141, v[42:45] offset:35072
	s_waitcnt vmcnt(6)
	ds_write_b128 v141, v[46:49] offset:43264
.Lffn_skip2:
	s_waitcnt lgkmcnt(0)
	s_barrier
	v_mfma_f32_16x16x32_bf16 v[106:109], v[170:173], v[110:113], v[162:165]
	v_mfma_f32_16x16x32_bf16 v[110:113], v[174:177], v[110:113], v[166:169]
	s_cbranch_scc1 .LBB0_1060
	s_add_i32 s20, s29, 1
	s_cmp_ge_i32 s20, s28
	s_cbranch_scc1 .LBB0_1072
	s_lshl_b32 s18, s29, 3
	v_readlane_b32 s14, v254, 25
	s_add_i32 s37, s14, s18
	s_mul_i32 s18, s66, s20
	s_add_i32 s21, s94, s18
	s_mov_b32 s31, 0
	s_mov_b32 s33, 0
	s_branch .LBB0_1064
